# kr
# speedup vs baseline: 1.0105x; 1.0055x over previous
; template <int KR>
; DEVI void row_scales(const u16* __restrict__ base, int brow, float* rsb) {
;   const int tid = opaque_tid();
;   int row = tid >> 1, half = tid & 1;
;   const u32x4* pp = reinterpret_cast<const u32x4*>(base + (size_t)(brow + row) * PJ_LD + half * (KR / 2));
;   float ss = 0.f;
; #pragma unroll 4
;   for (int i = 0; i < KR / 16; ++i) {
;     u32x4 v = pp[i];
; #pragma unroll
;     for (int q = 0; q < 4; ++q) {
;       float a = __uint_as_float(v[q] << 16), b = __uint_as_float(v[q] & 0xFFFF0000u);
;       ss += a * a + b * b;
;     }
;   }
;   ss += __shfl_xor(ss, 1);
;   if (half == 0) rsb[row] = rsqrtf(ss * (1.0f / KR) + 1e-6f);
; }
.LBB0_529:
	v_lshl_add_u64 v[44:45], v[0:1], 0, s[2:3]
	global_load_dwordx4 v[32:35], v[44:45], off offset:16
	global_load_dwordx4 v[36:39], v[44:45], off
	global_load_dwordx4 v[40:43], v[44:45], off offset:-16
	global_load_dwordx4 v[44:47], v[44:45], off offset:-32
	s_add_u32 s2, s2, 64
	s_addc_u32 s3, s3, 0
	v_lshl_add_u64 v[60:61], v[0:1], 0, s[2:3]
	global_load_dwordx4 v[48:51], v[60:61], off offset:16
	global_load_dwordx4 v[52:55], v[60:61], off
	global_load_dwordx4 v[56:59], v[60:61], off offset:-16
	global_load_dwordx4 v[60:63], v[60:61], off offset:-32
	s_add_u32 s2, s2, 64
	s_addc_u32 s3, s3, 0
	v_lshl_add_u64 v[76:77], v[0:1], 0, s[2:3]
	global_load_dwordx4 v[64:67], v[76:77], off offset:16
	global_load_dwordx4 v[68:71], v[76:77], off
	global_load_dwordx4 v[72:75], v[76:77], off offset:-16
	global_load_dwordx4 v[76:79], v[76:77], off offset:-32
	s_add_u32 s2, s2, 64
	s_addc_u32 s3, s3, 0
	v_lshl_add_u64 v[92:93], v[0:1], 0, s[2:3]
	global_load_dwordx4 v[80:83], v[92:93], off offset:16
	global_load_dwordx4 v[84:87], v[92:93], off
	global_load_dwordx4 v[88:91], v[92:93], off offset:-16
	global_load_dwordx4 v[92:95], v[92:93], off offset:-32
	s_add_u32 s2, s2, 64
	s_addc_u32 s3, s3, 0
	v_lshl_add_u64 v[108:109], v[0:1], 0, s[2:3]
	global_load_dwordx4 v[96:99], v[108:109], off offset:16
	global_load_dwordx4 v[100:103], v[108:109], off
	global_load_dwordx4 v[104:107], v[108:109], off offset:-16
	global_load_dwordx4 v[108:111], v[108:109], off offset:-32
	s_add_u32 s2, s2, 64
	s_addc_u32 s3, s3, 0
	v_lshl_add_u64 v[124:125], v[0:1], 0, s[2:3]
	global_load_dwordx4 v[112:115], v[124:125], off offset:16
	global_load_dwordx4 v[116:119], v[124:125], off
	global_load_dwordx4 v[120:123], v[124:125], off offset:-16
	global_load_dwordx4 v[124:127], v[124:125], off offset:-32
	s_add_u32 s2, s2, 64
	s_addc_u32 s3, s3, 0
	s_waitcnt vmcnt(20)
	v_lshlrev_b32_e32 v22, 16, v44
	v_and_b32_e32 v23, 0xffff0000, v44
	v_pk_mul_f32 v[22:23], v[22:23], v[22:23]
	s_nop 0
	v_add_f32_e32 v5, v22, v23
	v_and_b32_e32 v23, 0xffff0000, v46
	v_and_b32_e32 v22, 0xffff0000, v45
	v_add_f32_e32 v24, v4, v5
	v_lshlrev_b32_e32 v5, 16, v46
	v_lshlrev_b32_e32 v4, 16, v45
	v_pk_mul_f32 v[44:45], v[22:23], v[22:23]
	s_nop 0
	v_pk_fma_f32 v[4:5], v[4:5], v[4:5], v[44:45]
	v_and_b32_e32 v45, 0xffff0000, v42
	v_add_f32_e32 v4, v4, v24
	v_add_f32_e32 v44, v5, v4
	v_lshlrev_b32_e32 v4, 16, v47
	v_and_b32_e32 v5, 0xffff0000, v47
	v_pk_mul_f32 v[4:5], v[4:5], v[4:5]
	s_nop 0
	v_add_f32_e32 v4, v4, v5
	v_add_f32_e32 v44, v4, v44
	v_lshlrev_b32_e32 v4, 16, v40
	v_and_b32_e32 v5, 0xffff0000, v40
	v_pk_mul_f32 v[4:5], v[4:5], v[4:5]
	s_nop 0
	v_add_f32_e32 v4, v4, v5
	v_add_f32_e32 v46, v44, v4
	v_and_b32_e32 v44, 0xffff0000, v41
	v_lshlrev_b32_e32 v5, 16, v42
	v_lshlrev_b32_e32 v4, 16, v41
	v_pk_mul_f32 v[40:41], v[44:45], v[44:45]
	s_nop 0
	v_pk_fma_f32 v[4:5], v[4:5], v[4:5], v[40:41]
	v_and_b32_e32 v41, 0xffff0000, v38
	v_add_f32_e32 v4, v4, v46
	v_add_f32_e32 v40, v5, v4
	v_lshlrev_b32_e32 v4, 16, v43
	v_and_b32_e32 v5, 0xffff0000, v43
	v_pk_mul_f32 v[4:5], v[4:5], v[4:5]
	s_nop 0
	v_add_f32_e32 v4, v4, v5
	v_add_f32_e32 v40, v4, v40
	v_lshlrev_b32_e32 v4, 16, v36
	v_and_b32_e32 v5, 0xffff0000, v36
	v_pk_mul_f32 v[4:5], v[4:5], v[4:5]
	s_nop 0
	v_add_f32_e32 v4, v4, v5
	v_add_f32_e32 v42, v40, v4
	v_and_b32_e32 v40, 0xffff0000, v37
	v_lshlrev_b32_e32 v5, 16, v38
	v_lshlrev_b32_e32 v4, 16, v37
	v_pk_mul_f32 v[36:37], v[40:41], v[40:41]
	s_nop 0
	v_pk_fma_f32 v[4:5], v[4:5], v[4:5], v[36:37]
	v_and_b32_e32 v37, 0xffff0000, v34
	v_add_f32_e32 v4, v4, v42
	v_add_f32_e32 v36, v5, v4
	v_lshlrev_b32_e32 v4, 16, v39
	v_and_b32_e32 v5, 0xffff0000, v39
	v_pk_mul_f32 v[4:5], v[4:5], v[4:5]
	s_nop 0
	v_add_f32_e32 v4, v4, v5
	v_add_f32_e32 v36, v4, v36
	v_lshlrev_b32_e32 v4, 16, v32
	v_and_b32_e32 v5, 0xffff0000, v32
	v_pk_mul_f32 v[4:5], v[4:5], v[4:5]
	s_nop 0
	v_add_f32_e32 v4, v4, v5
	v_add_f32_e32 v38, v36, v4
	v_and_b32_e32 v36, 0xffff0000, v33
	v_lshlrev_b32_e32 v5, 16, v34
	v_lshlrev_b32_e32 v4, 16, v33
	v_pk_mul_f32 v[32:33], v[36:37], v[36:37]
	s_nop 0
	v_pk_fma_f32 v[4:5], v[4:5], v[4:5], v[32:33]
	s_nop 0
	v_add_f32_e32 v4, v4, v38
	v_add_f32_e32 v32, v5, v4
	v_lshlrev_b32_e32 v4, 16, v35
	v_and_b32_e32 v5, 0xffff0000, v35
	v_pk_mul_f32 v[4:5], v[4:5], v[4:5]
	s_nop 0
	v_add_f32_e32 v4, v4, v5
	v_add_f32_e32 v4, v4, v32
	s_waitcnt vmcnt(16)
	v_lshlrev_b32_e32 v22, 16, v60
	v_and_b32_e32 v23, 0xffff0000, v60
	v_pk_mul_f32 v[22:23], v[22:23], v[22:23]
	s_nop 0
	v_add_f32_e32 v5, v22, v23
	v_and_b32_e32 v23, 0xffff0000, v62
	v_and_b32_e32 v22, 0xffff0000, v61
	v_add_f32_e32 v24, v4, v5
	v_lshlrev_b32_e32 v5, 16, v62
	v_lshlrev_b32_e32 v4, 16, v61
	v_pk_mul_f32 v[60:61], v[22:23], v[22:23]
	s_nop 0
	v_pk_fma_f32 v[4:5], v[4:5], v[4:5], v[60:61]
	v_and_b32_e32 v61, 0xffff0000, v58
	v_add_f32_e32 v4, v4, v24
	v_add_f32_e32 v60, v5, v4
	v_lshlrev_b32_e32 v4, 16, v63
	v_and_b32_e32 v5, 0xffff0000, v63
	v_pk_mul_f32 v[4:5], v[4:5], v[4:5]
	s_nop 0
	v_add_f32_e32 v4, v4, v5
	v_add_f32_e32 v60, v4, v60
	v_lshlrev_b32_e32 v4, 16, v56
	v_and_b32_e32 v5, 0xffff0000, v56
	v_pk_mul_f32 v[4:5], v[4:5], v[4:5]
	s_nop 0
	v_add_f32_e32 v4, v4, v5
	v_add_f32_e32 v62, v60, v4
	v_and_b32_e32 v60, 0xffff0000, v57
	v_lshlrev_b32_e32 v5, 16, v58
	v_lshlrev_b32_e32 v4, 16, v57
	v_pk_mul_f32 v[56:57], v[60:61], v[60:61]
	s_nop 0
	v_pk_fma_f32 v[4:5], v[4:5], v[4:5], v[56:57]
	v_and_b32_e32 v57, 0xffff0000, v54
	v_add_f32_e32 v4, v4, v62
	v_add_f32_e32 v56, v5, v4
	v_lshlrev_b32_e32 v4, 16, v59
	v_and_b32_e32 v5, 0xffff0000, v59
	v_pk_mul_f32 v[4:5], v[4:5], v[4:5]
	s_nop 0
	v_add_f32_e32 v4, v4, v5
	v_add_f32_e32 v56, v4, v56
	v_lshlrev_b32_e32 v4, 16, v52
	v_and_b32_e32 v5, 0xffff0000, v52
	v_pk_mul_f32 v[4:5], v[4:5], v[4:5]
	s_nop 0
	v_add_f32_e32 v4, v4, v5
	v_add_f32_e32 v58, v56, v4
	v_and_b32_e32 v56, 0xffff0000, v53
	v_lshlrev_b32_e32 v5, 16, v54
	v_lshlrev_b32_e32 v4, 16, v53
	v_pk_mul_f32 v[52:53], v[56:57], v[56:57]
	s_nop 0
	v_pk_fma_f32 v[4:5], v[4:5], v[4:5], v[52:53]
	v_and_b32_e32 v53, 0xffff0000, v50
	v_add_f32_e32 v4, v4, v58
	v_add_f32_e32 v52, v5, v4
	v_lshlrev_b32_e32 v4, 16, v55
	v_and_b32_e32 v5, 0xffff0000, v55
	v_pk_mul_f32 v[4:5], v[4:5], v[4:5]
	s_nop 0
	v_add_f32_e32 v4, v4, v5
	v_add_f32_e32 v52, v4, v52
	v_lshlrev_b32_e32 v4, 16, v48
	v_and_b32_e32 v5, 0xffff0000, v48
	v_pk_mul_f32 v[4:5], v[4:5], v[4:5]
	s_nop 0
	v_add_f32_e32 v4, v4, v5
	v_add_f32_e32 v54, v52, v4
	v_and_b32_e32 v52, 0xffff0000, v49
	v_lshlrev_b32_e32 v5, 16, v50
	v_lshlrev_b32_e32 v4, 16, v49
	v_pk_mul_f32 v[48:49], v[52:53], v[52:53]
	s_nop 0
	v_pk_fma_f32 v[4:5], v[4:5], v[4:5], v[48:49]
	s_nop 0
	v_add_f32_e32 v4, v4, v54
	v_add_f32_e32 v48, v5, v4
	v_lshlrev_b32_e32 v4, 16, v51
	v_and_b32_e32 v5, 0xffff0000, v51
	v_pk_mul_f32 v[4:5], v[4:5], v[4:5]
	s_nop 0
	v_add_f32_e32 v4, v4, v5
	v_add_f32_e32 v4, v4, v48
	s_waitcnt vmcnt(12)
; template <int KR>
; DEVI void row_scales(const u16* __restrict__ base, int brow, float* rsb) {
;     ...
;   const u32x4* pp = reinterpret_cast<const u32x4*>(base + (size_t)(brow + row) * PJ_LD + half * (KR / 2));
;   float ss = 0.f;
; #pragma unroll 4
;   for (int i = 0; i < KR / 16; ++i) {
;     u32x4 v = pp[i];
; #pragma unroll
;     for (int q = 0; q < 4; ++q) {
;       float a = __uint_as_float(v[q] << 16), b = __uint_as_float(v[q] & 0xFFFF0000u);
;       ss += a * a + b * b;
;     }
;   }
	v_lshlrev_b32_e32 v22, 16, v76
	v_and_b32_e32 v23, 0xffff0000, v76
	v_pk_mul_f32 v[22:23], v[22:23], v[22:23]
	s_nop 0
	v_add_f32_e32 v5, v22, v23
	v_and_b32_e32 v23, 0xffff0000, v78
	v_and_b32_e32 v22, 0xffff0000, v77
	v_add_f32_e32 v24, v4, v5
	v_lshlrev_b32_e32 v5, 16, v78
	v_lshlrev_b32_e32 v4, 16, v77
	v_pk_mul_f32 v[76:77], v[22:23], v[22:23]
	s_nop 0
	v_pk_fma_f32 v[4:5], v[4:5], v[4:5], v[76:77]
	v_and_b32_e32 v77, 0xffff0000, v74
	v_add_f32_e32 v4, v4, v24
	v_add_f32_e32 v76, v5, v4
	v_lshlrev_b32_e32 v4, 16, v79
	v_and_b32_e32 v5, 0xffff0000, v79
	v_pk_mul_f32 v[4:5], v[4:5], v[4:5]
	s_nop 0
	v_add_f32_e32 v4, v4, v5
	v_add_f32_e32 v76, v4, v76
	v_lshlrev_b32_e32 v4, 16, v72
	v_and_b32_e32 v5, 0xffff0000, v72
	v_pk_mul_f32 v[4:5], v[4:5], v[4:5]
	s_nop 0
	v_add_f32_e32 v4, v4, v5
	v_add_f32_e32 v78, v76, v4
	v_and_b32_e32 v76, 0xffff0000, v73
	v_lshlrev_b32_e32 v5, 16, v74
	v_lshlrev_b32_e32 v4, 16, v73
	v_pk_mul_f32 v[72:73], v[76:77], v[76:77]
	s_nop 0
	v_pk_fma_f32 v[4:5], v[4:5], v[4:5], v[72:73]
	v_and_b32_e32 v73, 0xffff0000, v70
	v_add_f32_e32 v4, v4, v78
	v_add_f32_e32 v72, v5, v4
	v_lshlrev_b32_e32 v4, 16, v75
	v_and_b32_e32 v5, 0xffff0000, v75
	v_pk_mul_f32 v[4:5], v[4:5], v[4:5]
	s_nop 0
	v_add_f32_e32 v4, v4, v5
	v_add_f32_e32 v72, v4, v72
	v_lshlrev_b32_e32 v4, 16, v68
	v_and_b32_e32 v5, 0xffff0000, v68
	v_pk_mul_f32 v[4:5], v[4:5], v[4:5]
	s_nop 0
	v_add_f32_e32 v4, v4, v5
	v_add_f32_e32 v74, v72, v4
	v_and_b32_e32 v72, 0xffff0000, v69
	v_lshlrev_b32_e32 v5, 16, v70
	v_lshlrev_b32_e32 v4, 16, v69
	v_pk_mul_f32 v[68:69], v[72:73], v[72:73]
	s_nop 0
	v_pk_fma_f32 v[4:5], v[4:5], v[4:5], v[68:69]
	v_and_b32_e32 v69, 0xffff0000, v66
	v_add_f32_e32 v4, v4, v74
	v_add_f32_e32 v68, v5, v4
	v_lshlrev_b32_e32 v4, 16, v71
	v_and_b32_e32 v5, 0xffff0000, v71
	v_pk_mul_f32 v[4:5], v[4:5], v[4:5]
	s_nop 0
	v_add_f32_e32 v4, v4, v5
	v_add_f32_e32 v68, v4, v68
	v_lshlrev_b32_e32 v4, 16, v64
	v_and_b32_e32 v5, 0xffff0000, v64
	v_pk_mul_f32 v[4:5], v[4:5], v[4:5]
	s_nop 0
	v_add_f32_e32 v4, v4, v5
	v_add_f32_e32 v70, v68, v4
	v_and_b32_e32 v68, 0xffff0000, v65
	v_lshlrev_b32_e32 v5, 16, v66
	v_lshlrev_b32_e32 v4, 16, v65
	v_pk_mul_f32 v[64:65], v[68:69], v[68:69]
	s_nop 0
	v_pk_fma_f32 v[4:5], v[4:5], v[4:5], v[64:65]
	s_nop 0
	v_add_f32_e32 v4, v4, v70
	v_add_f32_e32 v64, v5, v4
	v_lshlrev_b32_e32 v4, 16, v67
	v_and_b32_e32 v5, 0xffff0000, v67
	v_pk_mul_f32 v[4:5], v[4:5], v[4:5]
	s_nop 0
	v_add_f32_e32 v4, v4, v5
	v_add_f32_e32 v4, v4, v64
	s_waitcnt vmcnt(8)
	v_lshlrev_b32_e32 v22, 16, v92
	v_and_b32_e32 v23, 0xffff0000, v92
	v_pk_mul_f32 v[22:23], v[22:23], v[22:23]
	s_nop 0
	v_add_f32_e32 v5, v22, v23
	v_and_b32_e32 v23, 0xffff0000, v94
	v_and_b32_e32 v22, 0xffff0000, v93
	v_add_f32_e32 v24, v4, v5
	v_lshlrev_b32_e32 v5, 16, v94
	v_lshlrev_b32_e32 v4, 16, v93
	v_pk_mul_f32 v[92:93], v[22:23], v[22:23]
	s_nop 0
	v_pk_fma_f32 v[4:5], v[4:5], v[4:5], v[92:93]
	v_and_b32_e32 v93, 0xffff0000, v90
	v_add_f32_e32 v4, v4, v24
	v_add_f32_e32 v92, v5, v4
	v_lshlrev_b32_e32 v4, 16, v95
	v_and_b32_e32 v5, 0xffff0000, v95
	v_pk_mul_f32 v[4:5], v[4:5], v[4:5]
	s_nop 0
	v_add_f32_e32 v4, v4, v5
	v_add_f32_e32 v92, v4, v92
	v_lshlrev_b32_e32 v4, 16, v88
	v_and_b32_e32 v5, 0xffff0000, v88
	v_pk_mul_f32 v[4:5], v[4:5], v[4:5]
	s_nop 0
	v_add_f32_e32 v4, v4, v5
	v_add_f32_e32 v94, v92, v4
	v_and_b32_e32 v92, 0xffff0000, v89
	v_lshlrev_b32_e32 v5, 16, v90
	v_lshlrev_b32_e32 v4, 16, v89
	v_pk_mul_f32 v[88:89], v[92:93], v[92:93]
	s_nop 0
	v_pk_fma_f32 v[4:5], v[4:5], v[4:5], v[88:89]
	v_and_b32_e32 v89, 0xffff0000, v86
	v_add_f32_e32 v4, v4, v94
	v_add_f32_e32 v88, v5, v4
	v_lshlrev_b32_e32 v4, 16, v91
	v_and_b32_e32 v5, 0xffff0000, v91
	v_pk_mul_f32 v[4:5], v[4:5], v[4:5]
	s_nop 0
	v_add_f32_e32 v4, v4, v5
	v_add_f32_e32 v88, v4, v88
	v_lshlrev_b32_e32 v4, 16, v84
	v_and_b32_e32 v5, 0xffff0000, v84
	v_pk_mul_f32 v[4:5], v[4:5], v[4:5]
	s_nop 0
	v_add_f32_e32 v4, v4, v5
	v_add_f32_e32 v90, v88, v4
	v_and_b32_e32 v88, 0xffff0000, v85
	v_lshlrev_b32_e32 v5, 16, v86
	v_lshlrev_b32_e32 v4, 16, v85
	v_pk_mul_f32 v[84:85], v[88:89], v[88:89]
	s_nop 0
	v_pk_fma_f32 v[4:5], v[4:5], v[4:5], v[84:85]
	v_and_b32_e32 v85, 0xffff0000, v82
	v_add_f32_e32 v4, v4, v90
	v_add_f32_e32 v84, v5, v4
	v_lshlrev_b32_e32 v4, 16, v87
	v_and_b32_e32 v5, 0xffff0000, v87
	v_pk_mul_f32 v[4:5], v[4:5], v[4:5]
	s_nop 0
	v_add_f32_e32 v4, v4, v5
	v_add_f32_e32 v84, v4, v84
	v_lshlrev_b32_e32 v4, 16, v80
	v_and_b32_e32 v5, 0xffff0000, v80
	v_pk_mul_f32 v[4:5], v[4:5], v[4:5]
	s_nop 0
	v_add_f32_e32 v4, v4, v5
	v_add_f32_e32 v86, v84, v4
	v_and_b32_e32 v84, 0xffff0000, v81
	v_lshlrev_b32_e32 v5, 16, v82
	v_lshlrev_b32_e32 v4, 16, v81
	v_pk_mul_f32 v[80:81], v[84:85], v[84:85]
	s_nop 0
	v_pk_fma_f32 v[4:5], v[4:5], v[4:5], v[80:81]
	s_nop 0
	v_add_f32_e32 v4, v4, v86
	v_add_f32_e32 v80, v5, v4
	v_lshlrev_b32_e32 v4, 16, v83
	v_and_b32_e32 v5, 0xffff0000, v83
	v_pk_mul_f32 v[4:5], v[4:5], v[4:5]
	s_nop 0
	v_add_f32_e32 v4, v4, v5
	v_add_f32_e32 v4, v4, v80
	s_waitcnt vmcnt(4)
; template <int KR>
; DEVI void row_scales(const u16* __restrict__ base, int brow, float* rsb) {
;     ...
;   const u32x4* pp = reinterpret_cast<const u32x4*>(base + (size_t)(brow + row) * PJ_LD + half * (KR / 2));
;   float ss = 0.f;
; #pragma unroll 4
;   for (int i = 0; i < KR / 16; ++i) {
;     u32x4 v = pp[i];
; #pragma unroll
;     for (int q = 0; q < 4; ++q) {
;       float a = __uint_as_float(v[q] << 16), b = __uint_as_float(v[q] & 0xFFFF0000u);
;       ss += a * a + b * b;
;     }
;   }
;   ss += __shfl_xor(ss, 1);
;   if (half == 0) rsb[row] = rsqrtf(ss * (1.0f / KR) + 1e-6f);
; }
	v_lshlrev_b32_e32 v22, 16, v108
	v_and_b32_e32 v23, 0xffff0000, v108
	v_pk_mul_f32 v[22:23], v[22:23], v[22:23]
	s_nop 0
	v_add_f32_e32 v5, v22, v23
	v_and_b32_e32 v23, 0xffff0000, v110
	v_and_b32_e32 v22, 0xffff0000, v109
	v_add_f32_e32 v24, v4, v5
	v_lshlrev_b32_e32 v5, 16, v110
	v_lshlrev_b32_e32 v4, 16, v109
	v_pk_mul_f32 v[108:109], v[22:23], v[22:23]
	s_nop 0
	v_pk_fma_f32 v[4:5], v[4:5], v[4:5], v[108:109]
	v_and_b32_e32 v109, 0xffff0000, v106
	v_add_f32_e32 v4, v4, v24
	v_add_f32_e32 v108, v5, v4
	v_lshlrev_b32_e32 v4, 16, v111
	v_and_b32_e32 v5, 0xffff0000, v111
	v_pk_mul_f32 v[4:5], v[4:5], v[4:5]
	s_nop 0
	v_add_f32_e32 v4, v4, v5
	v_add_f32_e32 v108, v4, v108
	v_lshlrev_b32_e32 v4, 16, v104
	v_and_b32_e32 v5, 0xffff0000, v104
	v_pk_mul_f32 v[4:5], v[4:5], v[4:5]
	s_nop 0
	v_add_f32_e32 v4, v4, v5
	v_add_f32_e32 v110, v108, v4
	v_and_b32_e32 v108, 0xffff0000, v105
	v_lshlrev_b32_e32 v5, 16, v106
	v_lshlrev_b32_e32 v4, 16, v105
	v_pk_mul_f32 v[104:105], v[108:109], v[108:109]
	s_nop 0
	v_pk_fma_f32 v[4:5], v[4:5], v[4:5], v[104:105]
	v_and_b32_e32 v105, 0xffff0000, v102
	v_add_f32_e32 v4, v4, v110
	v_add_f32_e32 v104, v5, v4
	v_lshlrev_b32_e32 v4, 16, v107
	v_and_b32_e32 v5, 0xffff0000, v107
	v_pk_mul_f32 v[4:5], v[4:5], v[4:5]
	s_nop 0
	v_add_f32_e32 v4, v4, v5
	v_add_f32_e32 v104, v4, v104
	v_lshlrev_b32_e32 v4, 16, v100
	v_and_b32_e32 v5, 0xffff0000, v100
	v_pk_mul_f32 v[4:5], v[4:5], v[4:5]
	s_nop 0
	v_add_f32_e32 v4, v4, v5
	v_add_f32_e32 v106, v104, v4
	v_and_b32_e32 v104, 0xffff0000, v101
	v_lshlrev_b32_e32 v5, 16, v102
	v_lshlrev_b32_e32 v4, 16, v101
	v_pk_mul_f32 v[100:101], v[104:105], v[104:105]
	s_nop 0
	v_pk_fma_f32 v[4:5], v[4:5], v[4:5], v[100:101]
	v_and_b32_e32 v101, 0xffff0000, v98
	v_add_f32_e32 v4, v4, v106
	v_add_f32_e32 v100, v5, v4
	v_lshlrev_b32_e32 v4, 16, v103
	v_and_b32_e32 v5, 0xffff0000, v103
	v_pk_mul_f32 v[4:5], v[4:5], v[4:5]
	s_nop 0
	v_add_f32_e32 v4, v4, v5
	v_add_f32_e32 v100, v4, v100
	v_lshlrev_b32_e32 v4, 16, v96
	v_and_b32_e32 v5, 0xffff0000, v96
	v_pk_mul_f32 v[4:5], v[4:5], v[4:5]
	s_nop 0
	v_add_f32_e32 v4, v4, v5
	v_add_f32_e32 v102, v100, v4
	v_and_b32_e32 v100, 0xffff0000, v97
	v_lshlrev_b32_e32 v5, 16, v98
	v_lshlrev_b32_e32 v4, 16, v97
	v_pk_mul_f32 v[96:97], v[100:101], v[100:101]
	s_nop 0
	v_pk_fma_f32 v[4:5], v[4:5], v[4:5], v[96:97]
	s_nop 0
	v_add_f32_e32 v4, v4, v102
	v_add_f32_e32 v96, v5, v4
	v_lshlrev_b32_e32 v4, 16, v99
	v_and_b32_e32 v5, 0xffff0000, v99
	v_pk_mul_f32 v[4:5], v[4:5], v[4:5]
	s_nop 0
	v_add_f32_e32 v4, v4, v5
	v_add_f32_e32 v4, v4, v96
	s_waitcnt vmcnt(0)
	v_lshlrev_b32_e32 v22, 16, v124
	v_and_b32_e32 v23, 0xffff0000, v124
	v_pk_mul_f32 v[22:23], v[22:23], v[22:23]
	s_nop 0
	v_add_f32_e32 v5, v22, v23
	v_and_b32_e32 v23, 0xffff0000, v126
	v_and_b32_e32 v22, 0xffff0000, v125
	v_add_f32_e32 v24, v4, v5
	v_lshlrev_b32_e32 v5, 16, v126
	v_lshlrev_b32_e32 v4, 16, v125
	v_pk_mul_f32 v[124:125], v[22:23], v[22:23]
	s_nop 0
	v_pk_fma_f32 v[4:5], v[4:5], v[4:5], v[124:125]
	v_and_b32_e32 v125, 0xffff0000, v122
	v_add_f32_e32 v4, v4, v24
	v_add_f32_e32 v124, v5, v4
	v_lshlrev_b32_e32 v4, 16, v127
	v_and_b32_e32 v5, 0xffff0000, v127
	v_pk_mul_f32 v[4:5], v[4:5], v[4:5]
	s_nop 0
	v_add_f32_e32 v4, v4, v5
	v_add_f32_e32 v124, v4, v124
	v_lshlrev_b32_e32 v4, 16, v120
	v_and_b32_e32 v5, 0xffff0000, v120
	v_pk_mul_f32 v[4:5], v[4:5], v[4:5]
	s_nop 0
	v_add_f32_e32 v4, v4, v5
	v_add_f32_e32 v126, v124, v4
	v_and_b32_e32 v124, 0xffff0000, v121
	v_lshlrev_b32_e32 v5, 16, v122
	v_lshlrev_b32_e32 v4, 16, v121
	v_pk_mul_f32 v[120:121], v[124:125], v[124:125]
	s_nop 0
	v_pk_fma_f32 v[4:5], v[4:5], v[4:5], v[120:121]
	v_and_b32_e32 v121, 0xffff0000, v118
	v_add_f32_e32 v4, v4, v126
	v_add_f32_e32 v120, v5, v4
	v_lshlrev_b32_e32 v4, 16, v123
	v_and_b32_e32 v5, 0xffff0000, v123
	v_pk_mul_f32 v[4:5], v[4:5], v[4:5]
	s_nop 0
	v_add_f32_e32 v4, v4, v5
	v_add_f32_e32 v120, v4, v120
	v_lshlrev_b32_e32 v4, 16, v116
	v_and_b32_e32 v5, 0xffff0000, v116
	v_pk_mul_f32 v[4:5], v[4:5], v[4:5]
	s_nop 0
	v_add_f32_e32 v4, v4, v5
	v_add_f32_e32 v122, v120, v4
	v_and_b32_e32 v120, 0xffff0000, v117
	v_lshlrev_b32_e32 v5, 16, v118
	v_lshlrev_b32_e32 v4, 16, v117
	v_pk_mul_f32 v[116:117], v[120:121], v[120:121]
	s_nop 0
	v_pk_fma_f32 v[4:5], v[4:5], v[4:5], v[116:117]
	v_and_b32_e32 v117, 0xffff0000, v114
	v_add_f32_e32 v4, v4, v122
	v_add_f32_e32 v116, v5, v4
	v_lshlrev_b32_e32 v4, 16, v119
	v_and_b32_e32 v5, 0xffff0000, v119
	v_pk_mul_f32 v[4:5], v[4:5], v[4:5]
	s_nop 0
	v_add_f32_e32 v4, v4, v5
	v_add_f32_e32 v116, v4, v116
	v_lshlrev_b32_e32 v4, 16, v112
	v_and_b32_e32 v5, 0xffff0000, v112
	v_pk_mul_f32 v[4:5], v[4:5], v[4:5]
	s_nop 0
	v_add_f32_e32 v4, v4, v5
	v_add_f32_e32 v118, v116, v4
	v_and_b32_e32 v116, 0xffff0000, v113
	v_lshlrev_b32_e32 v5, 16, v114
	v_lshlrev_b32_e32 v4, 16, v113
	v_pk_mul_f32 v[112:113], v[116:117], v[116:117]
	s_nop 0
	v_pk_fma_f32 v[4:5], v[4:5], v[4:5], v[112:113]
	s_nop 0
	v_add_f32_e32 v4, v4, v118
	v_add_f32_e32 v112, v5, v4
	v_lshlrev_b32_e32 v4, 16, v115
	v_and_b32_e32 v5, 0xffff0000, v115
	v_pk_mul_f32 v[4:5], v[4:5], v[4:5]
	s_nop 0
	v_add_f32_e32 v4, v4, v5
	v_add_f32_e32 v4, v4, v112
	v_and_b32_e32 v1, 64, v140
	v_xor_b32_e32 v0, 1, v140
	v_add_u32_e32 v1, 64, v1
	v_cmp_lt_i32_e32 vcc, v0, v1
	s_nop 1
	v_cndmask_b32_e32 v0, v140, v0, vcc
	v_lshlrev_b32_e32 v0, 2, v0
	ds_bpermute_b32 v0, v0, v4
	v_cmp_eq_u32_e32 vcc, 0, v3
	s_and_saveexec_b64 s[2:3], vcc
	s_cbranch_execz .LBB0_532
	s_waitcnt lgkmcnt(0)
	v_add_f32_e32 v0, v4, v0
	v_fmamk_f32 v0, v0, 0x3b2aaaab, v138
	v_mul_f32_e32 v1, 0x4b800000, v0
	v_cmp_gt_f32_e32 vcc, s85, v0
	s_nop 1
	v_cndmask_b32_e32 v0, v0, v1, vcc
	v_rsq_f32_e32 v0, v0
	v_lshl_add_u32 v1, v2, 2, 0
	v_add_u32_e32 v1, 0x20000, v1
	v_mul_f32_e32 v2, 0x45800000, v0
	v_cndmask_b32_e32 v0, v0, v2, vcc
	ds_write_b32 v1, v0

; template <int KR>
; DEVI void row_scales(const u16* __restrict__ base, int brow, float* rsb) {
;   const int tid = opaque_tid();
;   int row = tid >> 1, half = tid & 1;
;   const u32x4* pp = reinterpret_cast<const u32x4*>(base + (size_t)(brow + row) * PJ_LD + half * (KR / 2));
;   float ss = 0.f;
; #pragma unroll 4
;   for (int i = 0; i < KR / 16; ++i) {
;     u32x4 v = pp[i];
; #pragma unroll
;     for (int q = 0; q < 4; ++q) {
;       float a = __uint_as_float(v[q] << 16), b = __uint_as_float(v[q] & 0xFFFF0000u);
;       ss += a * a + b * b;
;     }
;   }
.LBB0_747:
	v_lshl_add_u64 v[44:45], v[2:3], 0, s[2:3]
	global_load_dwordx4 v[32:35], v[44:45], off offset:16
	global_load_dwordx4 v[36:39], v[44:45], off
	global_load_dwordx4 v[40:43], v[44:45], off offset:-16
	global_load_dwordx4 v[44:47], v[44:45], off offset:-32
	s_add_u32 s2, s2, 64
	s_addc_u32 s3, s3, 0
	v_lshl_add_u64 v[60:61], v[2:3], 0, s[2:3]
	global_load_dwordx4 v[48:51], v[60:61], off offset:16
	global_load_dwordx4 v[52:55], v[60:61], off
	global_load_dwordx4 v[56:59], v[60:61], off offset:-16
	global_load_dwordx4 v[60:63], v[60:61], off offset:-32
	s_add_u32 s2, s2, 64
	s_addc_u32 s3, s3, 0
	v_lshl_add_u64 v[76:77], v[2:3], 0, s[2:3]
	global_load_dwordx4 v[64:67], v[76:77], off offset:16
	global_load_dwordx4 v[68:71], v[76:77], off
	global_load_dwordx4 v[72:75], v[76:77], off offset:-16
	global_load_dwordx4 v[76:79], v[76:77], off offset:-32
	s_add_u32 s2, s2, 64
	s_addc_u32 s3, s3, 0
	v_lshl_add_u64 v[92:93], v[2:3], 0, s[2:3]
	global_load_dwordx4 v[80:83], v[92:93], off offset:16
	global_load_dwordx4 v[84:87], v[92:93], off
	global_load_dwordx4 v[88:91], v[92:93], off offset:-16
	global_load_dwordx4 v[92:95], v[92:93], off offset:-32
	s_add_u32 s2, s2, 64
	s_addc_u32 s3, s3, 0
	s_waitcnt vmcnt(12)
	v_lshlrev_b32_e32 v22, 16, v44
	v_and_b32_e32 v23, 0xffff0000, v44
	v_pk_mul_f32 v[22:23], v[22:23], v[22:23]
	s_nop 0
	v_add_f32_e32 v5, v22, v23
	v_and_b32_e32 v23, 0xffff0000, v46
	v_and_b32_e32 v22, 0xffff0000, v45
	v_add_f32_e32 v24, v4, v5
	v_lshlrev_b32_e32 v5, 16, v46
	v_lshlrev_b32_e32 v4, 16, v45
	v_pk_mul_f32 v[44:45], v[22:23], v[22:23]
	s_nop 0
	v_pk_fma_f32 v[4:5], v[4:5], v[4:5], v[44:45]
	v_and_b32_e32 v45, 0xffff0000, v42
	v_add_f32_e32 v4, v4, v24
	v_add_f32_e32 v44, v5, v4
	v_lshlrev_b32_e32 v4, 16, v47
	v_and_b32_e32 v5, 0xffff0000, v47
	v_pk_mul_f32 v[4:5], v[4:5], v[4:5]
	s_nop 0
	v_add_f32_e32 v4, v4, v5
	v_add_f32_e32 v44, v4, v44
	v_lshlrev_b32_e32 v4, 16, v40
	v_and_b32_e32 v5, 0xffff0000, v40
	v_pk_mul_f32 v[4:5], v[4:5], v[4:5]
	s_nop 0
	v_add_f32_e32 v4, v4, v5
	v_add_f32_e32 v46, v44, v4
	v_and_b32_e32 v44, 0xffff0000, v41
	v_lshlrev_b32_e32 v5, 16, v42
	v_lshlrev_b32_e32 v4, 16, v41
	v_pk_mul_f32 v[40:41], v[44:45], v[44:45]
	s_nop 0
	v_pk_fma_f32 v[4:5], v[4:5], v[4:5], v[40:41]
	v_and_b32_e32 v41, 0xffff0000, v38
	v_add_f32_e32 v4, v4, v46
	v_add_f32_e32 v40, v5, v4
	v_lshlrev_b32_e32 v4, 16, v43
	v_and_b32_e32 v5, 0xffff0000, v43
	v_pk_mul_f32 v[4:5], v[4:5], v[4:5]
	s_nop 0
	v_add_f32_e32 v4, v4, v5
	v_add_f32_e32 v40, v4, v40
	v_lshlrev_b32_e32 v4, 16, v36
	v_and_b32_e32 v5, 0xffff0000, v36
	v_pk_mul_f32 v[4:5], v[4:5], v[4:5]
	s_nop 0
	v_add_f32_e32 v4, v4, v5
	v_add_f32_e32 v42, v40, v4
	v_and_b32_e32 v40, 0xffff0000, v37
	v_lshlrev_b32_e32 v5, 16, v38
	v_lshlrev_b32_e32 v4, 16, v37
	v_pk_mul_f32 v[36:37], v[40:41], v[40:41]
	s_nop 0
	v_pk_fma_f32 v[4:5], v[4:5], v[4:5], v[36:37]
	v_and_b32_e32 v37, 0xffff0000, v34
	v_add_f32_e32 v4, v4, v42
	v_add_f32_e32 v36, v5, v4
	v_lshlrev_b32_e32 v4, 16, v39
	v_and_b32_e32 v5, 0xffff0000, v39
	v_pk_mul_f32 v[4:5], v[4:5], v[4:5]
	s_nop 0
	v_add_f32_e32 v4, v4, v5
	v_add_f32_e32 v36, v4, v36
	v_lshlrev_b32_e32 v4, 16, v32
	v_and_b32_e32 v5, 0xffff0000, v32
	v_pk_mul_f32 v[4:5], v[4:5], v[4:5]
	s_nop 0
	v_add_f32_e32 v4, v4, v5
	v_add_f32_e32 v38, v36, v4
	v_and_b32_e32 v36, 0xffff0000, v33
	v_lshlrev_b32_e32 v5, 16, v34
	v_lshlrev_b32_e32 v4, 16, v33
	v_pk_mul_f32 v[32:33], v[36:37], v[36:37]
	s_nop 0
	v_pk_fma_f32 v[4:5], v[4:5], v[4:5], v[32:33]
	s_nop 0
	v_add_f32_e32 v4, v4, v38
	v_add_f32_e32 v32, v5, v4
	v_lshlrev_b32_e32 v4, 16, v35
	v_and_b32_e32 v5, 0xffff0000, v35
	v_pk_mul_f32 v[4:5], v[4:5], v[4:5]
	s_nop 0
	v_add_f32_e32 v4, v4, v5
	v_add_f32_e32 v4, v4, v32
	s_waitcnt vmcnt(8)
	v_lshlrev_b32_e32 v22, 16, v60
	v_and_b32_e32 v23, 0xffff0000, v60
	v_pk_mul_f32 v[22:23], v[22:23], v[22:23]
	s_nop 0
	v_add_f32_e32 v5, v22, v23
	v_and_b32_e32 v23, 0xffff0000, v62
	v_and_b32_e32 v22, 0xffff0000, v61
	v_add_f32_e32 v24, v4, v5
	v_lshlrev_b32_e32 v5, 16, v62
	v_lshlrev_b32_e32 v4, 16, v61
	v_pk_mul_f32 v[60:61], v[22:23], v[22:23]
	s_nop 0
	v_pk_fma_f32 v[4:5], v[4:5], v[4:5], v[60:61]
	v_and_b32_e32 v61, 0xffff0000, v58
	v_add_f32_e32 v4, v4, v24
	v_add_f32_e32 v60, v5, v4
	v_lshlrev_b32_e32 v4, 16, v63
	v_and_b32_e32 v5, 0xffff0000, v63
	v_pk_mul_f32 v[4:5], v[4:5], v[4:5]
	s_nop 0
	v_add_f32_e32 v4, v4, v5
	v_add_f32_e32 v60, v4, v60
	v_lshlrev_b32_e32 v4, 16, v56
	v_and_b32_e32 v5, 0xffff0000, v56
	v_pk_mul_f32 v[4:5], v[4:5], v[4:5]
	s_nop 0
	v_add_f32_e32 v4, v4, v5
	v_add_f32_e32 v62, v60, v4
	v_and_b32_e32 v60, 0xffff0000, v57
	v_lshlrev_b32_e32 v5, 16, v58
	v_lshlrev_b32_e32 v4, 16, v57
	v_pk_mul_f32 v[56:57], v[60:61], v[60:61]
	s_nop 0
	v_pk_fma_f32 v[4:5], v[4:5], v[4:5], v[56:57]
	v_and_b32_e32 v57, 0xffff0000, v54
	v_add_f32_e32 v4, v4, v62
	v_add_f32_e32 v56, v5, v4
	v_lshlrev_b32_e32 v4, 16, v59
	v_and_b32_e32 v5, 0xffff0000, v59
	v_pk_mul_f32 v[4:5], v[4:5], v[4:5]
	s_nop 0
	v_add_f32_e32 v4, v4, v5
	v_add_f32_e32 v56, v4, v56
	v_lshlrev_b32_e32 v4, 16, v52
	v_and_b32_e32 v5, 0xffff0000, v52
	v_pk_mul_f32 v[4:5], v[4:5], v[4:5]
	s_nop 0
	v_add_f32_e32 v4, v4, v5
	v_add_f32_e32 v58, v56, v4
	v_and_b32_e32 v56, 0xffff0000, v53
	v_lshlrev_b32_e32 v5, 16, v54
	v_lshlrev_b32_e32 v4, 16, v53
	v_pk_mul_f32 v[52:53], v[56:57], v[56:57]
	s_nop 0
	v_pk_fma_f32 v[4:5], v[4:5], v[4:5], v[52:53]
	v_and_b32_e32 v53, 0xffff0000, v50
	v_add_f32_e32 v4, v4, v58
	v_add_f32_e32 v52, v5, v4
	v_lshlrev_b32_e32 v4, 16, v55
	v_and_b32_e32 v5, 0xffff0000, v55
	v_pk_mul_f32 v[4:5], v[4:5], v[4:5]
	s_nop 0
	v_add_f32_e32 v4, v4, v5
	v_add_f32_e32 v52, v4, v52
	v_lshlrev_b32_e32 v4, 16, v48
	v_and_b32_e32 v5, 0xffff0000, v48
	v_pk_mul_f32 v[4:5], v[4:5], v[4:5]
	s_nop 0
	v_add_f32_e32 v4, v4, v5
	v_add_f32_e32 v54, v52, v4
	v_and_b32_e32 v52, 0xffff0000, v49
	v_lshlrev_b32_e32 v5, 16, v50
	v_lshlrev_b32_e32 v4, 16, v49
	v_pk_mul_f32 v[48:49], v[52:53], v[52:53]
	s_nop 0
	v_pk_fma_f32 v[4:5], v[4:5], v[4:5], v[48:49]
	s_nop 0
	v_add_f32_e32 v4, v4, v54
	v_add_f32_e32 v48, v5, v4
	v_lshlrev_b32_e32 v4, 16, v51
	v_and_b32_e32 v5, 0xffff0000, v51
	v_pk_mul_f32 v[4:5], v[4:5], v[4:5]
	s_nop 0
	v_add_f32_e32 v4, v4, v5
	v_add_f32_e32 v4, v4, v48
	s_waitcnt vmcnt(4)
; template <int KR>
; DEVI void row_scales(const u16* __restrict__ base, int brow, float* rsb) {
;     ...
;   const u32x4* pp = reinterpret_cast<const u32x4*>(base + (size_t)(brow + row) * PJ_LD + half * (KR / 2));
;   float ss = 0.f;
; #pragma unroll 4
;   for (int i = 0; i < KR / 16; ++i) {
;     u32x4 v = pp[i];
; #pragma unroll
;     for (int q = 0; q < 4; ++q) {
;       float a = __uint_as_float(v[q] << 16), b = __uint_as_float(v[q] & 0xFFFF0000u);
;       ss += a * a + b * b;
;     }
;   }
;   ss += __shfl_xor(ss, 1);
;   if (half == 0) rsb[row] = rsqrtf(ss * (1.0f / KR) + 1e-6f);
; }
	v_lshlrev_b32_e32 v22, 16, v76
	v_and_b32_e32 v23, 0xffff0000, v76
	v_pk_mul_f32 v[22:23], v[22:23], v[22:23]
	s_nop 0
	v_add_f32_e32 v5, v22, v23
	v_and_b32_e32 v23, 0xffff0000, v78
	v_and_b32_e32 v22, 0xffff0000, v77
	v_add_f32_e32 v24, v4, v5
	v_lshlrev_b32_e32 v5, 16, v78
	v_lshlrev_b32_e32 v4, 16, v77
	v_pk_mul_f32 v[76:77], v[22:23], v[22:23]
	s_nop 0
	v_pk_fma_f32 v[4:5], v[4:5], v[4:5], v[76:77]
	v_and_b32_e32 v77, 0xffff0000, v74
	v_add_f32_e32 v4, v4, v24
	v_add_f32_e32 v76, v5, v4
	v_lshlrev_b32_e32 v4, 16, v79
	v_and_b32_e32 v5, 0xffff0000, v79
	v_pk_mul_f32 v[4:5], v[4:5], v[4:5]
	s_nop 0
	v_add_f32_e32 v4, v4, v5
	v_add_f32_e32 v76, v4, v76
	v_lshlrev_b32_e32 v4, 16, v72
	v_and_b32_e32 v5, 0xffff0000, v72
	v_pk_mul_f32 v[4:5], v[4:5], v[4:5]
	s_nop 0
	v_add_f32_e32 v4, v4, v5
	v_add_f32_e32 v78, v76, v4
	v_and_b32_e32 v76, 0xffff0000, v73
	v_lshlrev_b32_e32 v5, 16, v74
	v_lshlrev_b32_e32 v4, 16, v73
	v_pk_mul_f32 v[72:73], v[76:77], v[76:77]
	s_nop 0
	v_pk_fma_f32 v[4:5], v[4:5], v[4:5], v[72:73]
	v_and_b32_e32 v73, 0xffff0000, v70
	v_add_f32_e32 v4, v4, v78
	v_add_f32_e32 v72, v5, v4
	v_lshlrev_b32_e32 v4, 16, v75
	v_and_b32_e32 v5, 0xffff0000, v75
	v_pk_mul_f32 v[4:5], v[4:5], v[4:5]
	s_nop 0
	v_add_f32_e32 v4, v4, v5
	v_add_f32_e32 v72, v4, v72
	v_lshlrev_b32_e32 v4, 16, v68
	v_and_b32_e32 v5, 0xffff0000, v68
	v_pk_mul_f32 v[4:5], v[4:5], v[4:5]
	s_nop 0
	v_add_f32_e32 v4, v4, v5
	v_add_f32_e32 v74, v72, v4
	v_and_b32_e32 v72, 0xffff0000, v69
	v_lshlrev_b32_e32 v5, 16, v70
	v_lshlrev_b32_e32 v4, 16, v69
	v_pk_mul_f32 v[68:69], v[72:73], v[72:73]
	s_nop 0
	v_pk_fma_f32 v[4:5], v[4:5], v[4:5], v[68:69]
	v_and_b32_e32 v69, 0xffff0000, v66
	v_add_f32_e32 v4, v4, v74
	v_add_f32_e32 v68, v5, v4
	v_lshlrev_b32_e32 v4, 16, v71
	v_and_b32_e32 v5, 0xffff0000, v71
	v_pk_mul_f32 v[4:5], v[4:5], v[4:5]
	s_nop 0
	v_add_f32_e32 v4, v4, v5
	v_add_f32_e32 v68, v4, v68
	v_lshlrev_b32_e32 v4, 16, v64
	v_and_b32_e32 v5, 0xffff0000, v64
	v_pk_mul_f32 v[4:5], v[4:5], v[4:5]
	s_nop 0
	v_add_f32_e32 v4, v4, v5
	v_add_f32_e32 v70, v68, v4
	v_and_b32_e32 v68, 0xffff0000, v65
	v_lshlrev_b32_e32 v5, 16, v66
	v_lshlrev_b32_e32 v4, 16, v65
	v_pk_mul_f32 v[64:65], v[68:69], v[68:69]
	s_nop 0
	v_pk_fma_f32 v[4:5], v[4:5], v[4:5], v[64:65]
	s_nop 0
	v_add_f32_e32 v4, v4, v70
	v_add_f32_e32 v64, v5, v4
	v_lshlrev_b32_e32 v4, 16, v67
	v_and_b32_e32 v5, 0xffff0000, v67
	v_pk_mul_f32 v[4:5], v[4:5], v[4:5]
	s_nop 0
	v_add_f32_e32 v4, v4, v5
	v_add_f32_e32 v4, v4, v64
	s_waitcnt vmcnt(0)
	v_lshlrev_b32_e32 v22, 16, v92
	v_and_b32_e32 v23, 0xffff0000, v92
	v_pk_mul_f32 v[22:23], v[22:23], v[22:23]
	s_nop 0
	v_add_f32_e32 v5, v22, v23
	v_and_b32_e32 v23, 0xffff0000, v94
	v_and_b32_e32 v22, 0xffff0000, v93
	v_add_f32_e32 v24, v4, v5
	v_lshlrev_b32_e32 v5, 16, v94
	v_lshlrev_b32_e32 v4, 16, v93
	v_pk_mul_f32 v[92:93], v[22:23], v[22:23]
	s_nop 0
	v_pk_fma_f32 v[4:5], v[4:5], v[4:5], v[92:93]
	v_and_b32_e32 v93, 0xffff0000, v90
	v_add_f32_e32 v4, v4, v24
	v_add_f32_e32 v92, v5, v4
	v_lshlrev_b32_e32 v4, 16, v95
	v_and_b32_e32 v5, 0xffff0000, v95
	v_pk_mul_f32 v[4:5], v[4:5], v[4:5]
	s_nop 0
	v_add_f32_e32 v4, v4, v5
	v_add_f32_e32 v92, v4, v92
	v_lshlrev_b32_e32 v4, 16, v88
	v_and_b32_e32 v5, 0xffff0000, v88
	v_pk_mul_f32 v[4:5], v[4:5], v[4:5]
	s_nop 0
	v_add_f32_e32 v4, v4, v5
	v_add_f32_e32 v94, v92, v4
	v_and_b32_e32 v92, 0xffff0000, v89
	v_lshlrev_b32_e32 v5, 16, v90
	v_lshlrev_b32_e32 v4, 16, v89
	v_pk_mul_f32 v[88:89], v[92:93], v[92:93]
	s_nop 0
	v_pk_fma_f32 v[4:5], v[4:5], v[4:5], v[88:89]
	v_and_b32_e32 v89, 0xffff0000, v86
	v_add_f32_e32 v4, v4, v94
	v_add_f32_e32 v88, v5, v4
	v_lshlrev_b32_e32 v4, 16, v91
	v_and_b32_e32 v5, 0xffff0000, v91
	v_pk_mul_f32 v[4:5], v[4:5], v[4:5]
	s_nop 0
	v_add_f32_e32 v4, v4, v5
	v_add_f32_e32 v88, v4, v88
	v_lshlrev_b32_e32 v4, 16, v84
	v_and_b32_e32 v5, 0xffff0000, v84
	v_pk_mul_f32 v[4:5], v[4:5], v[4:5]
	s_nop 0
	v_add_f32_e32 v4, v4, v5
	v_add_f32_e32 v90, v88, v4
	v_and_b32_e32 v88, 0xffff0000, v85
	v_lshlrev_b32_e32 v5, 16, v86
	v_lshlrev_b32_e32 v4, 16, v85
	v_pk_mul_f32 v[84:85], v[88:89], v[88:89]
	s_nop 0
	v_pk_fma_f32 v[4:5], v[4:5], v[4:5], v[84:85]
	v_and_b32_e32 v85, 0xffff0000, v82
	v_add_f32_e32 v4, v4, v90
	v_add_f32_e32 v84, v5, v4
	v_lshlrev_b32_e32 v4, 16, v87
	v_and_b32_e32 v5, 0xffff0000, v87
	v_pk_mul_f32 v[4:5], v[4:5], v[4:5]
	s_nop 0
	v_add_f32_e32 v4, v4, v5
	v_add_f32_e32 v84, v4, v84
	v_lshlrev_b32_e32 v4, 16, v80
	v_and_b32_e32 v5, 0xffff0000, v80
	v_pk_mul_f32 v[4:5], v[4:5], v[4:5]
	s_nop 0
	v_add_f32_e32 v4, v4, v5
	v_add_f32_e32 v86, v84, v4
	v_and_b32_e32 v84, 0xffff0000, v81
	v_lshlrev_b32_e32 v5, 16, v82
	v_lshlrev_b32_e32 v4, 16, v81
	v_pk_mul_f32 v[80:81], v[84:85], v[84:85]
	s_nop 0
	v_pk_fma_f32 v[4:5], v[4:5], v[4:5], v[80:81]
	s_nop 0
	v_add_f32_e32 v4, v4, v86
	v_add_f32_e32 v80, v5, v4
	v_lshlrev_b32_e32 v4, 16, v83
	v_and_b32_e32 v5, 0xffff0000, v83
	v_pk_mul_f32 v[4:5], v[4:5], v[4:5]
	s_nop 0
	v_add_f32_e32 v4, v4, v5
	v_add_f32_e32 v4, v4, v80
	v_and_b32_e32 v3, 64, v140
	v_xor_b32_e32 v2, 1, v140
	v_add_u32_e32 v3, 64, v3
	v_cmp_lt_i32_e32 vcc, v2, v3
	s_nop 1
	v_cndmask_b32_e32 v2, v140, v2, vcc
	v_lshlrev_b32_e32 v2, 2, v2
	ds_bpermute_b32 v2, v2, v4
	v_cmp_eq_u32_e32 vcc, 0, v1
	s_and_saveexec_b64 s[2:3], vcc
	s_cbranch_execz .LBB0_750
	s_waitcnt lgkmcnt(0)
	v_add_f32_e32 v1, v4, v2
	v_fmamk_f32 v1, v1, 0x3b800000, v138
	v_mul_f32_e32 v2, 0x4b800000, v1
	v_cmp_gt_f32_e32 vcc, s85, v1
	v_lshl_add_u32 v0, v0, 2, 0
	v_add_u32_e32 v0, 0x20000, v0
	v_cndmask_b32_e32 v1, v1, v2, vcc
	v_rsq_f32_e32 v1, v1
	s_nop 0
	v_mul_f32_e32 v2, 0x45800000, v1
	v_cndmask_b32_e32 v1, v1, v2, vcc
	ds_write_b32 v0, v1

; DEVI float bf2f(u16 h) { return __uint_as_float(((unsigned)h) << 16); }
; DEVI void phase2(const Params& p, char* shm) {
;     ...
;         for (int q = opaque_tid(); q < 4096; q += NTHR) {
;           int rl = q >> 4, i = q & 15;
;           int row = brow + rl;
;           float x1 = bf2f(projb[(size_t)row * PJ_LD + PJ_KR + i]);
;           float x2 = bf2f(projb[(size_t)row * PJ_LD + PJ_KR + 16 + i]);
;           float2 cs = tab[(row & 4095) * 16 + i];
;           u16 o1 = f2bf(x1 * cs.x - x2 * cs.y), o2 = f2bf(x1 * cs.y + x2 * cs.x);
; #pragma unroll
;           for (int h = 0; h < 8; ++h) {
;             Kb[(size_t)row * 768 + h * 96 + 64 + i] = o1;
;             Kb[(size_t)row * 768 + h * 96 + 80 + i] = o2;
;           }
;         }
.LBB0_759:
	v_ashrrev_i32_e32 v6, 4, v4
	v_add_u32_e32 v32, s79, v6
	v_mad_i64_i32 v[38:39], s[64:65], v32, s57, v[0:1]
	global_load_ushort v33, v[38:39], off offset:2816
	global_load_ushort v34, v[38:39], off offset:2848
	v_lshlrev_b32_e32 v6, 4, v32
	v_and_or_b32 v6, v6, s71, v5
	v_lshlrev_b32_e32 v6, 3, v6
	global_load_dwordx2 v[36:37], v6, s[22:23]
	v_add_u32_e32 v4, 0x200, v4
	v_ashrrev_i32_e32 v6, 4, v4
	v_add_u32_e32 v40, s79, v6
	v_mad_i64_i32 v[46:47], s[64:65], v40, s57, v[0:1]
	global_load_ushort v41, v[46:47], off offset:2816
	global_load_ushort v42, v[46:47], off offset:2848
	v_lshlrev_b32_e32 v6, 4, v40
	v_and_or_b32 v6, v6, s71, v5
	v_lshlrev_b32_e32 v6, 3, v6
	global_load_dwordx2 v[44:45], v6, s[22:23]
	v_add_u32_e32 v4, 0x200, v4
	v_ashrrev_i32_e32 v6, 4, v4
	v_add_u32_e32 v48, s79, v6
	v_mad_i64_i32 v[54:55], s[64:65], v48, s57, v[0:1]
	global_load_ushort v49, v[54:55], off offset:2816
	global_load_ushort v50, v[54:55], off offset:2848
	v_lshlrev_b32_e32 v6, 4, v48
	v_and_or_b32 v6, v6, s71, v5
	v_lshlrev_b32_e32 v6, 3, v6
	global_load_dwordx2 v[52:53], v6, s[22:23]
	v_add_u32_e32 v4, 0x200, v4
	v_ashrrev_i32_e32 v6, 4, v4
	v_add_u32_e32 v56, s79, v6
	v_mad_i64_i32 v[62:63], s[64:65], v56, s57, v[0:1]
	global_load_ushort v57, v[62:63], off offset:2816
	global_load_ushort v58, v[62:63], off offset:2848
	v_lshlrev_b32_e32 v6, 4, v56
	v_and_or_b32 v6, v6, s71, v5
	v_lshlrev_b32_e32 v6, 3, v6
	global_load_dwordx2 v[60:61], v6, s[22:23]
	v_add_u32_e32 v4, 0x200, v4
	v_ashrrev_i32_e32 v6, 4, v4
	v_add_u32_e32 v64, s79, v6
	v_mad_i64_i32 v[70:71], s[64:65], v64, s57, v[0:1]
	global_load_ushort v65, v[70:71], off offset:2816
	global_load_ushort v66, v[70:71], off offset:2848
	v_lshlrev_b32_e32 v6, 4, v64
	v_and_or_b32 v6, v6, s71, v5
	v_lshlrev_b32_e32 v6, 3, v6
	global_load_dwordx2 v[68:69], v6, s[22:23]
	v_add_u32_e32 v4, 0x200, v4
	v_ashrrev_i32_e32 v6, 4, v4
	v_add_u32_e32 v72, s79, v6
	v_mad_i64_i32 v[78:79], s[64:65], v72, s57, v[0:1]
	global_load_ushort v73, v[78:79], off offset:2816
	global_load_ushort v74, v[78:79], off offset:2848
	v_lshlrev_b32_e32 v6, 4, v72
	v_and_or_b32 v6, v6, s71, v5
	v_lshlrev_b32_e32 v6, 3, v6
	global_load_dwordx2 v[76:77], v6, s[22:23]
	v_add_u32_e32 v4, 0x200, v4
	v_ashrrev_i32_e32 v6, 4, v4
	v_add_u32_e32 v80, s79, v6
	v_mad_i64_i32 v[86:87], s[64:65], v80, s57, v[0:1]
	global_load_ushort v81, v[86:87], off offset:2816
	global_load_ushort v82, v[86:87], off offset:2848
	v_lshlrev_b32_e32 v6, 4, v80
	v_and_or_b32 v6, v6, s71, v5
	v_lshlrev_b32_e32 v6, 3, v6
	global_load_dwordx2 v[84:85], v6, s[22:23]
	v_add_u32_e32 v4, 0x200, v4
	v_ashrrev_i32_e32 v6, 4, v4
	v_add_u32_e32 v88, s79, v6
	v_mad_i64_i32 v[94:95], s[64:65], v88, s57, v[0:1]
	global_load_ushort v89, v[94:95], off offset:2816
	global_load_ushort v90, v[94:95], off offset:2848
	v_lshlrev_b32_e32 v6, 4, v88
	v_and_or_b32 v6, v6, s71, v5
	v_lshlrev_b32_e32 v6, 3, v6
	global_load_dwordx2 v[92:93], v6, s[22:23]
	v_add_u32_e32 v4, 0x200, v4
	s_waitcnt vmcnt(21)
	v_lshlrev_b32_e32 v9, 16, v33
	v_lshlrev_b32_e32 v10, 16, v34
	v_mul_f32_e32 v11, v37, v10
	v_fma_f32 v11, v36, v9, -v11
	v_mul_f32_e32 v7, v36, v10
	v_fmac_f32_e32 v7, v37, v9
	v_bfe_u32 v12, v11, 16, 1
	v_bfe_u32 v6, v7, 16, 1
	v_add3_u32 v11, v11, v12, s74
	v_add3_u32 v7, v7, v6, s74
	v_lshrrev_b32_e32 v33, 16, v11
	v_lshrrev_b32_e32 v34, 16, v7
	s_waitcnt vmcnt(18)
	v_lshlrev_b32_e32 v9, 16, v41
	v_lshlrev_b32_e32 v10, 16, v42
	v_mul_f32_e32 v11, v45, v10
	v_fma_f32 v11, v44, v9, -v11
	v_mul_f32_e32 v7, v44, v10
	v_fmac_f32_e32 v7, v45, v9
	v_bfe_u32 v12, v11, 16, 1
	v_bfe_u32 v6, v7, 16, 1
	v_add3_u32 v11, v11, v12, s74
	v_add3_u32 v7, v7, v6, s74
	v_lshrrev_b32_e32 v41, 16, v11
	v_lshrrev_b32_e32 v42, 16, v7
	s_waitcnt vmcnt(15)
	v_lshlrev_b32_e32 v9, 16, v49
	v_lshlrev_b32_e32 v10, 16, v50
	v_mul_f32_e32 v11, v53, v10
	v_fma_f32 v11, v52, v9, -v11
	v_mul_f32_e32 v7, v52, v10
	v_fmac_f32_e32 v7, v53, v9
	v_bfe_u32 v12, v11, 16, 1
	v_bfe_u32 v6, v7, 16, 1
	v_add3_u32 v11, v11, v12, s74
	v_add3_u32 v7, v7, v6, s74
	v_lshrrev_b32_e32 v49, 16, v11
	v_lshrrev_b32_e32 v50, 16, v7
	s_waitcnt vmcnt(12)
	v_lshlrev_b32_e32 v9, 16, v57
	v_lshlrev_b32_e32 v10, 16, v58
	v_mul_f32_e32 v11, v61, v10
	v_fma_f32 v11, v60, v9, -v11
	v_mul_f32_e32 v7, v60, v10
	v_fmac_f32_e32 v7, v61, v9
	v_bfe_u32 v12, v11, 16, 1
	v_bfe_u32 v6, v7, 16, 1
	v_add3_u32 v11, v11, v12, s74
	v_add3_u32 v7, v7, v6, s74
	v_lshrrev_b32_e32 v57, 16, v11
	v_lshrrev_b32_e32 v58, 16, v7
	s_waitcnt vmcnt(9)
	v_lshlrev_b32_e32 v9, 16, v65
	v_lshlrev_b32_e32 v10, 16, v66
	v_mul_f32_e32 v11, v69, v10
	v_fma_f32 v11, v68, v9, -v11
	v_mul_f32_e32 v7, v68, v10
	v_fmac_f32_e32 v7, v69, v9
	v_bfe_u32 v12, v11, 16, 1
	v_bfe_u32 v6, v7, 16, 1
	v_add3_u32 v11, v11, v12, s74
	v_add3_u32 v7, v7, v6, s74
	v_lshrrev_b32_e32 v65, 16, v11
	v_lshrrev_b32_e32 v66, 16, v7
	s_waitcnt vmcnt(6)
	v_lshlrev_b32_e32 v9, 16, v73
	v_lshlrev_b32_e32 v10, 16, v74
	v_mul_f32_e32 v11, v77, v10
	v_fma_f32 v11, v76, v9, -v11
	v_mul_f32_e32 v7, v76, v10
	v_fmac_f32_e32 v7, v77, v9
	v_bfe_u32 v12, v11, 16, 1
	v_bfe_u32 v6, v7, 16, 1
	v_add3_u32 v11, v11, v12, s74
	v_add3_u32 v7, v7, v6, s74
	v_lshrrev_b32_e32 v73, 16, v11
	v_lshrrev_b32_e32 v74, 16, v7
	s_waitcnt vmcnt(3)
	v_lshlrev_b32_e32 v9, 16, v81
	v_lshlrev_b32_e32 v10, 16, v82
	v_mul_f32_e32 v11, v85, v10
	v_fma_f32 v11, v84, v9, -v11
	v_mul_f32_e32 v7, v84, v10
	v_fmac_f32_e32 v7, v85, v9
	v_bfe_u32 v12, v11, 16, 1
	v_bfe_u32 v6, v7, 16, 1
	v_add3_u32 v11, v11, v12, s74
	v_add3_u32 v7, v7, v6, s74
	v_lshrrev_b32_e32 v81, 16, v11
	v_lshrrev_b32_e32 v82, 16, v7
	s_waitcnt vmcnt(0)
; DEVI float bf2f(u16 h) { return __uint_as_float(((unsigned)h) << 16); }
; DEVI void phase2(const Params& p, char* shm) {
;     ...
;           int row = brow + rl;
;           float x1 = bf2f(projb[(size_t)row * PJ_LD + PJ_KR + i]);
;           float x2 = bf2f(projb[(size_t)row * PJ_LD + PJ_KR + 16 + i]);
;           float2 cs = tab[(row & 4095) * 16 + i];
;           u16 o1 = f2bf(x1 * cs.x - x2 * cs.y), o2 = f2bf(x1 * cs.y + x2 * cs.x);
; #pragma unroll
;           for (int h = 0; h < 8; ++h) {
;             Kb[(size_t)row * 768 + h * 96 + 64 + i] = o1;
;             Kb[(size_t)row * 768 + h * 96 + 80 + i] = o2;
;           }
	v_lshlrev_b32_e32 v9, 16, v89
	v_lshlrev_b32_e32 v10, 16, v90
	v_mul_f32_e32 v11, v93, v10
	v_fma_f32 v11, v92, v9, -v11
	v_mul_f32_e32 v7, v92, v10
	v_fmac_f32_e32 v7, v93, v9
	v_bfe_u32 v12, v11, 16, 1
	v_bfe_u32 v6, v7, 16, 1
	v_add3_u32 v11, v11, v12, s74
	v_add3_u32 v7, v7, v6, s74
	v_lshrrev_b32_e32 v89, 16, v11
	v_lshrrev_b32_e32 v90, 16, v7
	v_mad_i64_i32 v[6:7], s[64:65], v32, s59, v[2:3]
	global_store_short v[6:7], v33, off offset:128
	global_store_short v[6:7], v34, off offset:160
	global_store_short v[6:7], v33, off offset:320
	global_store_short v[6:7], v34, off offset:352
	global_store_short v[6:7], v33, off offset:512
	global_store_short v[6:7], v34, off offset:544
	global_store_short v[6:7], v33, off offset:704
	global_store_short v[6:7], v34, off offset:736
	global_store_short v[6:7], v33, off offset:896
	global_store_short v[6:7], v34, off offset:928
	global_store_short v[6:7], v33, off offset:1088
	global_store_short v[6:7], v34, off offset:1120
	global_store_short v[6:7], v33, off offset:1280
	global_store_short v[6:7], v34, off offset:1312
	global_store_short v[6:7], v33, off offset:1472
	global_store_short v[6:7], v34, off offset:1504
	v_mad_i64_i32 v[6:7], s[64:65], v40, s59, v[2:3]
	global_store_short v[6:7], v41, off offset:128
	global_store_short v[6:7], v42, off offset:160
	global_store_short v[6:7], v41, off offset:320
	global_store_short v[6:7], v42, off offset:352
	global_store_short v[6:7], v41, off offset:512
	global_store_short v[6:7], v42, off offset:544
	global_store_short v[6:7], v41, off offset:704
	global_store_short v[6:7], v42, off offset:736
	global_store_short v[6:7], v41, off offset:896
	global_store_short v[6:7], v42, off offset:928
	global_store_short v[6:7], v41, off offset:1088
	global_store_short v[6:7], v42, off offset:1120
	global_store_short v[6:7], v41, off offset:1280
	global_store_short v[6:7], v42, off offset:1312
	global_store_short v[6:7], v41, off offset:1472
	global_store_short v[6:7], v42, off offset:1504
	v_mad_i64_i32 v[6:7], s[64:65], v48, s59, v[2:3]
	global_store_short v[6:7], v49, off offset:128
	global_store_short v[6:7], v50, off offset:160
	global_store_short v[6:7], v49, off offset:320
	global_store_short v[6:7], v50, off offset:352
	global_store_short v[6:7], v49, off offset:512
	global_store_short v[6:7], v50, off offset:544
	global_store_short v[6:7], v49, off offset:704
	global_store_short v[6:7], v50, off offset:736
	global_store_short v[6:7], v49, off offset:896
	global_store_short v[6:7], v50, off offset:928
	global_store_short v[6:7], v49, off offset:1088
	global_store_short v[6:7], v50, off offset:1120
	global_store_short v[6:7], v49, off offset:1280
	global_store_short v[6:7], v50, off offset:1312
	global_store_short v[6:7], v49, off offset:1472
	global_store_short v[6:7], v50, off offset:1504
	v_mad_i64_i32 v[6:7], s[64:65], v56, s59, v[2:3]
	global_store_short v[6:7], v57, off offset:128
	global_store_short v[6:7], v58, off offset:160
	global_store_short v[6:7], v57, off offset:320
	global_store_short v[6:7], v58, off offset:352
	global_store_short v[6:7], v57, off offset:512
	global_store_short v[6:7], v58, off offset:544
	global_store_short v[6:7], v57, off offset:704
	global_store_short v[6:7], v58, off offset:736
	global_store_short v[6:7], v57, off offset:896
	global_store_short v[6:7], v58, off offset:928
	global_store_short v[6:7], v57, off offset:1088
	global_store_short v[6:7], v58, off offset:1120
	global_store_short v[6:7], v57, off offset:1280
	global_store_short v[6:7], v58, off offset:1312
	global_store_short v[6:7], v57, off offset:1472
	global_store_short v[6:7], v58, off offset:1504
	v_mad_i64_i32 v[6:7], s[64:65], v64, s59, v[2:3]
	global_store_short v[6:7], v65, off offset:128
	global_store_short v[6:7], v66, off offset:160
	global_store_short v[6:7], v65, off offset:320
	global_store_short v[6:7], v66, off offset:352
	global_store_short v[6:7], v65, off offset:512
	global_store_short v[6:7], v66, off offset:544
	global_store_short v[6:7], v65, off offset:704
	global_store_short v[6:7], v66, off offset:736
	global_store_short v[6:7], v65, off offset:896
	global_store_short v[6:7], v66, off offset:928
	global_store_short v[6:7], v65, off offset:1088
	global_store_short v[6:7], v66, off offset:1120
	global_store_short v[6:7], v65, off offset:1280
	global_store_short v[6:7], v66, off offset:1312
	global_store_short v[6:7], v65, off offset:1472
	global_store_short v[6:7], v66, off offset:1504
	v_mad_i64_i32 v[6:7], s[64:65], v72, s59, v[2:3]
	global_store_short v[6:7], v73, off offset:128
	global_store_short v[6:7], v74, off offset:160
	global_store_short v[6:7], v73, off offset:320
	global_store_short v[6:7], v74, off offset:352
	global_store_short v[6:7], v73, off offset:512
	global_store_short v[6:7], v74, off offset:544
	global_store_short v[6:7], v73, off offset:704
	global_store_short v[6:7], v74, off offset:736
	global_store_short v[6:7], v73, off offset:896
	global_store_short v[6:7], v74, off offset:928
	global_store_short v[6:7], v73, off offset:1088
	global_store_short v[6:7], v74, off offset:1120
	global_store_short v[6:7], v73, off offset:1280
	global_store_short v[6:7], v74, off offset:1312
	global_store_short v[6:7], v73, off offset:1472
	global_store_short v[6:7], v74, off offset:1504
	v_mad_i64_i32 v[6:7], s[64:65], v80, s59, v[2:3]
	global_store_short v[6:7], v81, off offset:128
	global_store_short v[6:7], v82, off offset:160
	global_store_short v[6:7], v81, off offset:320
	global_store_short v[6:7], v82, off offset:352
	global_store_short v[6:7], v81, off offset:512
	global_store_short v[6:7], v82, off offset:544
	global_store_short v[6:7], v81, off offset:704
	global_store_short v[6:7], v82, off offset:736
	global_store_short v[6:7], v81, off offset:896
	global_store_short v[6:7], v82, off offset:928
	global_store_short v[6:7], v81, off offset:1088
	global_store_short v[6:7], v82, off offset:1120
	global_store_short v[6:7], v81, off offset:1280
	global_store_short v[6:7], v82, off offset:1312
	global_store_short v[6:7], v81, off offset:1472
	global_store_short v[6:7], v82, off offset:1504
	v_mad_i64_i32 v[6:7], s[64:65], v88, s59, v[2:3]
	global_store_short v[6:7], v89, off offset:128
	global_store_short v[6:7], v90, off offset:160
	global_store_short v[6:7], v89, off offset:320
	global_store_short v[6:7], v90, off offset:352
	global_store_short v[6:7], v89, off offset:512
	global_store_short v[6:7], v90, off offset:544
	global_store_short v[6:7], v89, off offset:704
	global_store_short v[6:7], v90, off offset:736
	global_store_short v[6:7], v89, off offset:896
	global_store_short v[6:7], v90, off offset:928
	global_store_short v[6:7], v89, off offset:1088
	global_store_short v[6:7], v90, off offset:1120
	global_store_short v[6:7], v89, off offset:1280
	global_store_short v[6:7], v90, off offset:1312
	global_store_short v[6:7], v89, off offset:1472
	global_store_short v[6:7], v90, off offset:1504
